# P1 K loop: LDS-DMA stage loads in scalar-base + lane-offset form (no VALU address adds beside the partner's MFMA stream)
# baseline (speedup 1.0000x reference)
; #define PG8_STAGE(bufoff, gbase, voff) do { _Pragma("unroll") for (int _i = 0; _i < 2; ++_i) \
;         __builtin_amdgcn_global_load_lds((const unsigned*)((const char*)(gbase) + (voff)[_i]), (LAS unsigned*)(lds + (bufoff) + ldsw + _i * 8192), 16, 0, 0); } while (0)
; #define PG8_LDA(dst, b, h) do { _Pragma("unroll") for (int m = 0; m < 4; ++m) _Pragma("unroll") for (int k = 0; k < 2; ++k) dst[m][k] = *(const LAS bf16x8*)(lds + PG8_SA(b, h) + aoff + m * 2048 + k * 1024); } while (0)
; #define PG8_LDB(dst, b, h) do { _Pragma("unroll") for (int n = 0; n < 2; ++n) _Pragma("unroll") for (int k = 0; k < 2; ++k) dst[n][k] = *(const LAS bf16x8*)(lds + PG8_SB(b, h) + boff + n * 2048 + k * 1024); } while (0)
; #define PG8_MMA(ai, bj, At, Bt) do { __builtin_amdgcn_s_setprio(1); _Pragma("unroll") for (int m = 0; m < 4; ++m) _Pragma("unroll") for (int n = 0; n < 2; ++n) _Pragma("unroll") for (int k = 0; k < 2; ++k) \
;         acc[ai][bj][m][n] = __builtin_amdgcn_mfma_f32_16x16x32_bf16(Bt[n][k], At[m][k], acc[ai][bj][m][n], 0, 0, 0); __builtin_amdgcn_s_setprio(0); } while (0)
; #define PG8_WAIT_V(n) asm volatile("s_waitcnt vmcnt(" #n ")" ::: "memory")
; #define PG8_WAIT_L(n) asm volatile("s_waitcnt lgkmcnt(" #n ")" ::: "memory")
; #define PG8_BAR __builtin_amdgcn_s_barrier()
; #define PG8_SCHED __builtin_amdgcn_sched_barrier(0)
; template <class Epi, class Sched>
; DI void gemm_phase(LAS unsigned char* lds, const int K, const Sched& S, const Epi& E, const int wid) {
;     ...
;             const bool last = (t == nt - 2);
;             const char* a1 = cA + (size_t)(t + 1) * kstep;
;             const char* a2 = last ? nA : cA + (size_t)(t + 2) * kstep; const char* b2 = last ? nB : cB + (size_t)(t + 2) * kstep;
;             const char* a3 = a2 + kstep; const char* b3 = b2 + kstep;
;             if (last && has_next) S.a_ready(nxt);
;             PG8_LDB(B0, 0, 0); PG8_LDB(B1, 0, 1); PG8_SCHED; PG8_LDA(At, 0, 0); PG8_STAGE(PG8_SA(1, 1), a1 + hstep, voffA);
;             PG8_WAIT_V(8); PG8_WAIT_L(0); PG8_BAR; PG8_MMA(0, 0, At, B0); PG8_MMA(0, 1, At, B1); PG8_BAR; PG8_SCHED;
;             PG8_LDA(At, 0, 1); PG8_STAGE(PG8_SB(0, 0), b2, voffB); PG8_STAGE(PG8_SB(0, 1), b2 + hstep, voffB); PG8_STAGE(PG8_SA(0, 0), a2, voffA);
;             PG8_WAIT_V(8); PG8_WAIT_L(0); PG8_BAR; PG8_MMA(1, 0, At, B0); PG8_MMA(1, 1, At, B1); PG8_BAR; PG8_SCHED;
.LBB0_96:
	ds_read_b128 v[128:131], v179
	ds_read_b128 v[132:135], v179 offset:1024
	ds_read_b128 v[136:139], v179 offset:2048
	ds_read_b128 v[140:143], v179 offset:3072
	ds_read_b128 v[144:147], v180
	ds_read_b128 v[164:167], v180 offset:1024
	ds_read_b128 v[168:171], v180 offset:2048
	ds_read_b128 v[172:175], v180 offset:3072
	s_add_u32 s18, s4, 0xfff80080
	s_addc_u32 s19, s5, -1
	s_cmp_eq_u32 s17, 28
	s_cselect_b32 s69, s9, s19
	s_cselect_b32 s68, s10, s18
	s_cselect_b32 s57, s11, s16
	s_cselect_b32 s56, s14, s15
	s_add_i32 m0, s22, 0xc000
	ds_read_b128 v[184:187], v181
	ds_read_b128 v[188:191], v181 offset:1024
	ds_read_b128 v[192:195], v181 offset:2048
	ds_read_b128 v[196:199], v181 offset:3072
	ds_read_b128 v[200:203], v181 offset:4096
	ds_read_b128 v[208:211], v181 offset:5120
	ds_read_b128 v[212:215], v181 offset:6144
	ds_read_b128 v[216:219], v181 offset:7168
	global_load_lds_dwordx4 v156, s[4:5]
	s_add_i32 m0, s22, 0xe000
	s_nop 0
	global_load_lds_dwordx4 v158, s[4:5]
	s_waitcnt vmcnt(8)
	s_waitcnt lgkmcnt(0)
	s_barrier
	v_mfma_f32_16x16x32_bf16 v[124:127], v[128:131], v[184:187], v[124:127]
	v_mfma_f32_16x16x32_bf16 v[120:123], v[136:139], v[184:187], v[120:123]
	v_mfma_f32_16x16x32_bf16 v[116:119], v[128:131], v[192:195], v[116:119]
	v_mfma_f32_16x16x32_bf16 v[112:115], v[136:139], v[192:195], v[112:115]
	v_mfma_f32_16x16x32_bf16 v[100:103], v[128:131], v[200:203], v[100:103]
	v_mfma_f32_16x16x32_bf16 v[96:99], v[136:139], v[200:203], v[96:99]
	v_mfma_f32_16x16x32_bf16 v[84:87], v[128:131], v[212:215], v[84:87]
	v_mfma_f32_16x16x32_bf16 v[80:83], v[136:139], v[212:215], v[80:83]
	v_mfma_f32_16x16x32_bf16 v[124:127], v[132:135], v[188:191], v[124:127]
	v_mfma_f32_16x16x32_bf16 v[120:123], v[140:143], v[188:191], v[120:123]
	v_mfma_f32_16x16x32_bf16 v[116:119], v[132:135], v[196:199], v[116:119]
	v_mfma_f32_16x16x32_bf16 v[112:115], v[140:143], v[196:199], v[112:115]
	v_mfma_f32_16x16x32_bf16 v[100:103], v[132:135], v[208:211], v[100:103]
	v_mfma_f32_16x16x32_bf16 v[96:99], v[140:143], v[208:211], v[96:99]
	v_mfma_f32_16x16x32_bf16 v[84:87], v[132:135], v[216:219], v[84:87]
	v_mfma_f32_16x16x32_bf16 v[80:83], v[140:143], v[216:219], v[80:83]
	v_mfma_f32_16x16x32_bf16 v[108:111], v[144:147], v[184:187], v[108:111]
	v_mfma_f32_16x16x32_bf16 v[104:107], v[168:171], v[184:187], v[104:107]
	v_mfma_f32_16x16x32_bf16 v[92:95], v[144:147], v[192:195], v[92:95]
	v_mfma_f32_16x16x32_bf16 v[88:91], v[168:171], v[192:195], v[88:91]
	v_mfma_f32_16x16x32_bf16 v[76:79], v[144:147], v[200:203], v[76:79]
	v_mfma_f32_16x16x32_bf16 v[72:75], v[168:171], v[200:203], v[72:75]
	v_mfma_f32_16x16x32_bf16 v[68:71], v[144:147], v[212:215], v[68:71]
	v_mfma_f32_16x16x32_bf16 v[64:67], v[168:171], v[212:215], v[64:67]
	v_mfma_f32_16x16x32_bf16 v[108:111], v[164:167], v[188:191], v[108:111]
	v_mfma_f32_16x16x32_bf16 v[104:107], v[172:175], v[188:191], v[104:107]
	v_mfma_f32_16x16x32_bf16 v[92:95], v[164:167], v[196:199], v[92:95]
	v_mfma_f32_16x16x32_bf16 v[88:91], v[172:175], v[196:199], v[88:91]
	v_mfma_f32_16x16x32_bf16 v[76:79], v[164:167], v[208:211], v[76:79]
	v_mfma_f32_16x16x32_bf16 v[72:75], v[172:175], v[208:211], v[72:75]
	v_mfma_f32_16x16x32_bf16 v[68:71], v[164:167], v[216:219], v[68:71]
	v_mfma_f32_16x16x32_bf16 v[64:67], v[172:175], v[216:219], v[64:67]
	s_barrier
	s_add_i32 s18, s13, s95
	s_mov_b32 m0, s18
	ds_read_b128 v[184:187], v181 offset:16384
	ds_read_b128 v[188:191], v181 offset:17408
	ds_read_b128 v[192:195], v181 offset:18432
	ds_read_b128 v[196:199], v181 offset:19456
	ds_read_b128 v[200:203], v181 offset:20480
	ds_read_b128 v[208:211], v181 offset:21504
	ds_read_b128 v[212:215], v181 offset:22528
	ds_read_b128 v[216:219], v181 offset:23552
	global_load_lds_dwordx4 v150, s[56:57]
	s_add_i32 m0, s18, 0x2000
	s_add_u32 s18, s56, 0x80000
	s_addc_u32 s19, s57, 0
	s_add_i32 s20, s24, s95
	global_load_lds_dwordx4 v154, s[56:57]
	s_mov_b32 m0, s20
	s_nop 0
	global_load_lds_dwordx4 v150, s[18:19]
	s_add_i32 m0, s20, 0x2000
	s_nop 0
	global_load_lds_dwordx4 v154, s[18:19]
	s_mov_b32 m0, s22
	s_nop 0
	global_load_lds_dwordx4 v148, s[68:69]
	s_mov_b32 m0, s23
	s_nop 0
	global_load_lds_dwordx4 v152, s[68:69]
	s_waitcnt vmcnt(8)
	s_waitcnt lgkmcnt(0)
	s_barrier
	v_mfma_f32_16x16x32_bf16 v[60:63], v[128:131], v[184:187], v[60:63]
	v_mfma_f32_16x16x32_bf16 v[56:59], v[136:139], v[184:187], v[56:59]
	v_mfma_f32_16x16x32_bf16 v[52:55], v[128:131], v[192:195], v[52:55]
	v_mfma_f32_16x16x32_bf16 v[48:51], v[136:139], v[192:195], v[48:51]
	v_mfma_f32_16x16x32_bf16 v[36:39], v[128:131], v[200:203], v[36:39]
	v_mfma_f32_16x16x32_bf16 v[32:35], v[136:139], v[200:203], v[32:35]
	v_mfma_f32_16x16x32_bf16 v[20:23], v[128:131], v[212:215], v[20:23]
	v_mfma_f32_16x16x32_bf16 v[16:19], v[136:139], v[212:215], v[16:19]
	v_mfma_f32_16x16x32_bf16 v[60:63], v[132:135], v[188:191], v[60:63]
	v_mfma_f32_16x16x32_bf16 v[56:59], v[140:143], v[188:191], v[56:59]
	v_mfma_f32_16x16x32_bf16 v[52:55], v[132:135], v[196:199], v[52:55]
	v_mfma_f32_16x16x32_bf16 v[48:51], v[140:143], v[196:199], v[48:51]
	v_mfma_f32_16x16x32_bf16 v[36:39], v[132:135], v[208:211], v[36:39]
	v_mfma_f32_16x16x32_bf16 v[32:35], v[140:143], v[208:211], v[32:35]
	v_mfma_f32_16x16x32_bf16 v[20:23], v[132:135], v[216:219], v[20:23]
	v_mfma_f32_16x16x32_bf16 v[16:19], v[140:143], v[216:219], v[16:19]
	v_mfma_f32_16x16x32_bf16 v[44:47], v[144:147], v[184:187], v[44:47]
	v_mfma_f32_16x16x32_bf16 v[40:43], v[168:171], v[184:187], v[40:43]
	v_mfma_f32_16x16x32_bf16 v[28:31], v[144:147], v[192:195], v[28:31]
	v_mfma_f32_16x16x32_bf16 v[24:27], v[168:171], v[192:195], v[24:27]
	v_mfma_f32_16x16x32_bf16 v[12:15], v[144:147], v[200:203], v[12:15]
	v_mfma_f32_16x16x32_bf16 v[8:11], v[168:171], v[200:203], v[8:11]
	v_mfma_f32_16x16x32_bf16 v[4:7], v[144:147], v[212:215], v[4:7]
	v_mfma_f32_16x16x32_bf16 v[0:3], v[168:171], v[212:215], v[0:3]
	v_mfma_f32_16x16x32_bf16 v[44:47], v[164:167], v[188:191], v[44:47]
	v_mfma_f32_16x16x32_bf16 v[40:43], v[172:175], v[188:191], v[40:43]
	v_mfma_f32_16x16x32_bf16 v[28:31], v[164:167], v[196:199], v[28:31]
	v_mfma_f32_16x16x32_bf16 v[24:27], v[172:175], v[196:199], v[24:27]
	v_mfma_f32_16x16x32_bf16 v[12:15], v[164:167], v[208:211], v[12:15]
	v_mfma_f32_16x16x32_bf16 v[8:11], v[172:175], v[208:211], v[8:11]
	v_mfma_f32_16x16x32_bf16 v[4:7], v[164:167], v[216:219], v[4:7]
	v_mfma_f32_16x16x32_bf16 v[0:3], v[172:175], v[216:219], v[0:3]
	s_barrier
; #define PG8_STAGE(bufoff, gbase, voff) do { _Pragma("unroll") for (int _i = 0; _i < 2; ++_i) \
;         __builtin_amdgcn_global_load_lds((const unsigned*)((const char*)(gbase) + (voff)[_i]), (LAS unsigned*)(lds + (bufoff) + ldsw + _i * 8192), 16, 0, 0); } while (0)
; #define PG8_LDA(dst, b, h) do { _Pragma("unroll") for (int m = 0; m < 4; ++m) _Pragma("unroll") for (int k = 0; k < 2; ++k) dst[m][k] = *(const LAS bf16x8*)(lds + PG8_SA(b, h) + aoff + m * 2048 + k * 1024); } while (0)
; #define PG8_LDB(dst, b, h) do { _Pragma("unroll") for (int n = 0; n < 2; ++n) _Pragma("unroll") for (int k = 0; k < 2; ++k) dst[n][k] = *(const LAS bf16x8*)(lds + PG8_SB(b, h) + boff + n * 2048 + k * 1024); } while (0)
; #define PG8_MMA(ai, bj, At, Bt) do { __builtin_amdgcn_s_setprio(1); _Pragma("unroll") for (int m = 0; m < 4; ++m) _Pragma("unroll") for (int n = 0; n < 2; ++n) _Pragma("unroll") for (int k = 0; k < 2; ++k) \
;         acc[ai][bj][m][n] = __builtin_amdgcn_mfma_f32_16x16x32_bf16(Bt[n][k], At[m][k], acc[ai][bj][m][n], 0, 0, 0); __builtin_amdgcn_s_setprio(0); } while (0)
; #define PG8_WAIT_V(n) asm volatile("s_waitcnt vmcnt(" #n ")" ::: "memory")
; #define PG8_WAIT_L(n) asm volatile("s_waitcnt lgkmcnt(" #n ")" ::: "memory")
; #define PG8_BAR __builtin_amdgcn_s_barrier()
; #define PG8_SCHED __builtin_amdgcn_sched_barrier(0)
; template <class Epi, class Sched>
; DI void gemm_phase(LAS unsigned char* lds, const int K, const Sched& S, const Epi& E, const int wid) {
;     ...
;             PG8_LDB(B0, 1, 0); PG8_LDB(B1, 1, 1); PG8_SCHED; PG8_LDA(At, 1, 0); PG8_STAGE(PG8_SA(0, 1), a2 + hstep, voffA);
;             PG8_WAIT_V(8); PG8_WAIT_L(0); PG8_BAR; PG8_MMA(0, 0, At, B0); PG8_MMA(0, 1, At, B1); PG8_BAR; PG8_SCHED;
;             PG8_LDA(At, 1, 1); PG8_STAGE(PG8_SB(1, 0), b3, voffB); PG8_STAGE(PG8_SB(1, 1), b3 + hstep, voffB); PG8_STAGE(PG8_SA(1, 0), a3, voffA);
;             PG8_WAIT_V(8); PG8_WAIT_L(0); PG8_BAR; PG8_MMA(1, 0, At, B0); PG8_MMA(1, 1, At, B1); PG8_BAR; PG8_SCHED;
;         }
	s_add_i32 s20, 0, 0x18000
	s_add_i32 s21, 0, 0x1c000
	v_add_u32_e32 v140, s20, v178
	v_add_u32_e32 v172, s21, v178
	ds_read_b128 v[128:131], v140
	ds_read_b128 v[132:135], v140 offset:1024
	ds_read_b128 v[136:139], v140 offset:2048
	ds_read_b128 v[140:143], v140 offset:3072
	ds_read_b128 v[144:147], v172
	ds_read_b128 v[164:167], v172 offset:1024
	ds_read_b128 v[168:171], v172 offset:2048
	ds_read_b128 v[172:175], v172 offset:3072
	s_add_u32 s18, s68, 0x80000
	s_addc_u32 s19, s69, 0
	s_mov_b32 m0, s26
	ds_read_b128 v[184:187], v181 offset:32768
	ds_read_b128 v[188:191], v181 offset:33792
	ds_read_b128 v[192:195], v181 offset:34816
	ds_read_b128 v[196:199], v181 offset:35840
	ds_read_b128 v[200:203], v181 offset:36864
	ds_read_b128 v[208:211], v181 offset:37888
	ds_read_b128 v[212:215], v181 offset:38912
	ds_read_b128 v[216:219], v181 offset:39936
	global_load_lds_dwordx4 v148, s[18:19]
	s_mov_b32 m0, s27
	s_nop 0
	global_load_lds_dwordx4 v152, s[18:19]
	s_waitcnt vmcnt(8)
	s_waitcnt lgkmcnt(0)
	s_barrier
	v_mfma_f32_16x16x32_bf16 v[124:127], v[128:131], v[184:187], v[124:127]
	v_mfma_f32_16x16x32_bf16 v[120:123], v[136:139], v[184:187], v[120:123]
	v_mfma_f32_16x16x32_bf16 v[116:119], v[128:131], v[192:195], v[116:119]
	v_mfma_f32_16x16x32_bf16 v[112:115], v[136:139], v[192:195], v[112:115]
	v_mfma_f32_16x16x32_bf16 v[100:103], v[128:131], v[200:203], v[100:103]
	v_mfma_f32_16x16x32_bf16 v[96:99], v[136:139], v[200:203], v[96:99]
	v_mfma_f32_16x16x32_bf16 v[84:87], v[128:131], v[212:215], v[84:87]
	v_mfma_f32_16x16x32_bf16 v[80:83], v[136:139], v[212:215], v[80:83]
	v_mfma_f32_16x16x32_bf16 v[124:127], v[132:135], v[188:191], v[124:127]
	v_mfma_f32_16x16x32_bf16 v[120:123], v[140:143], v[188:191], v[120:123]
	v_mfma_f32_16x16x32_bf16 v[116:119], v[132:135], v[196:199], v[116:119]
	v_mfma_f32_16x16x32_bf16 v[112:115], v[140:143], v[196:199], v[112:115]
	v_mfma_f32_16x16x32_bf16 v[100:103], v[132:135], v[208:211], v[100:103]
	v_mfma_f32_16x16x32_bf16 v[96:99], v[140:143], v[208:211], v[96:99]
	v_mfma_f32_16x16x32_bf16 v[84:87], v[132:135], v[216:219], v[84:87]
	v_mfma_f32_16x16x32_bf16 v[80:83], v[140:143], v[216:219], v[80:83]
	v_mfma_f32_16x16x32_bf16 v[108:111], v[144:147], v[184:187], v[108:111]
	v_mfma_f32_16x16x32_bf16 v[104:107], v[168:171], v[184:187], v[104:107]
	v_mfma_f32_16x16x32_bf16 v[92:95], v[144:147], v[192:195], v[92:95]
	v_mfma_f32_16x16x32_bf16 v[88:91], v[168:171], v[192:195], v[88:91]
	v_mfma_f32_16x16x32_bf16 v[76:79], v[144:147], v[200:203], v[76:79]
	v_mfma_f32_16x16x32_bf16 v[72:75], v[168:171], v[200:203], v[72:75]
	v_mfma_f32_16x16x32_bf16 v[68:71], v[144:147], v[212:215], v[68:71]
	v_mfma_f32_16x16x32_bf16 v[64:67], v[168:171], v[212:215], v[64:67]
	v_mfma_f32_16x16x32_bf16 v[108:111], v[164:167], v[188:191], v[108:111]
	v_mfma_f32_16x16x32_bf16 v[104:107], v[172:175], v[188:191], v[104:107]
	v_mfma_f32_16x16x32_bf16 v[92:95], v[164:167], v[196:199], v[92:95]
	v_mfma_f32_16x16x32_bf16 v[88:91], v[172:175], v[196:199], v[88:91]
	v_mfma_f32_16x16x32_bf16 v[76:79], v[164:167], v[208:211], v[76:79]
	v_mfma_f32_16x16x32_bf16 v[72:75], v[172:175], v[208:211], v[72:75]
	v_mfma_f32_16x16x32_bf16 v[68:71], v[164:167], v[216:219], v[68:71]
	v_mfma_f32_16x16x32_bf16 v[64:67], v[172:175], v[216:219], v[64:67]
	s_barrier
	s_add_i32 s18, s20, s95
	s_mov_b32 m0, s18
	ds_read_b128 v[184:187], v181 offset:49152
	ds_read_b128 v[188:191], v181 offset:50176
	ds_read_b128 v[192:195], v181 offset:51200
	ds_read_b128 v[196:199], v181 offset:52224
	ds_read_b128 v[200:203], v181 offset:53248
	ds_read_b128 v[208:211], v181 offset:54272
	ds_read_b128 v[212:215], v181 offset:55296
	ds_read_b128 v[216:219], v181 offset:56320
	s_add_u32 s100, s56, s42
	s_addc_u32 s101, s57, s43
	global_load_lds_dwordx4 v150, s[100:101]
	s_add_i32 m0, s18, 0x2000
	s_add_u32 s18, s56, 0x80080
	s_addc_u32 s19, s57, 0
	s_add_i32 s20, s21, s95
	s_add_u32 s100, s56, s42
	s_addc_u32 s101, s57, s43
	global_load_lds_dwordx4 v154, s[100:101]
	s_mov_b32 m0, s20
	s_nop 0
	global_load_lds_dwordx4 v150, s[18:19]
	s_add_i32 m0, s20, 0x2000
	s_nop 0
	global_load_lds_dwordx4 v154, s[18:19]
	s_mov_b32 m0, s94
	s_nop 0
	s_add_u32 s100, s68, s42
	s_addc_u32 s101, s69, s43
	global_load_lds_dwordx4 v148, s[100:101]
	s_mov_b32 m0, s96
	s_nop 0
	s_add_u32 s100, s68, s42
	s_addc_u32 s101, s69, s43
	global_load_lds_dwordx4 v152, s[100:101]
	s_waitcnt vmcnt(8)
	s_waitcnt lgkmcnt(0)
	s_barrier
	v_mfma_f32_16x16x32_bf16 v[60:63], v[128:131], v[184:187], v[60:63]
	v_mfma_f32_16x16x32_bf16 v[56:59], v[136:139], v[184:187], v[56:59]
	v_mfma_f32_16x16x32_bf16 v[52:55], v[128:131], v[192:195], v[52:55]
	v_mfma_f32_16x16x32_bf16 v[48:51], v[136:139], v[192:195], v[48:51]
	v_mfma_f32_16x16x32_bf16 v[36:39], v[128:131], v[200:203], v[36:39]
	v_mfma_f32_16x16x32_bf16 v[32:35], v[136:139], v[200:203], v[32:35]
	v_mfma_f32_16x16x32_bf16 v[20:23], v[128:131], v[212:215], v[20:23]
	v_mfma_f32_16x16x32_bf16 v[16:19], v[136:139], v[212:215], v[16:19]
	v_mfma_f32_16x16x32_bf16 v[60:63], v[132:135], v[188:191], v[60:63]
	v_mfma_f32_16x16x32_bf16 v[56:59], v[140:143], v[188:191], v[56:59]
	v_mfma_f32_16x16x32_bf16 v[52:55], v[132:135], v[196:199], v[52:55]
	v_mfma_f32_16x16x32_bf16 v[48:51], v[140:143], v[196:199], v[48:51]
	v_mfma_f32_16x16x32_bf16 v[36:39], v[132:135], v[208:211], v[36:39]
	v_mfma_f32_16x16x32_bf16 v[32:35], v[140:143], v[208:211], v[32:35]
	v_mfma_f32_16x16x32_bf16 v[20:23], v[132:135], v[216:219], v[20:23]
	v_mfma_f32_16x16x32_bf16 v[16:19], v[140:143], v[216:219], v[16:19]
	v_mfma_f32_16x16x32_bf16 v[44:47], v[144:147], v[184:187], v[44:47]
	v_mfma_f32_16x16x32_bf16 v[40:43], v[168:171], v[184:187], v[40:43]
	v_mfma_f32_16x16x32_bf16 v[28:31], v[144:147], v[192:195], v[28:31]
	v_mfma_f32_16x16x32_bf16 v[24:27], v[168:171], v[192:195], v[24:27]
	v_mfma_f32_16x16x32_bf16 v[12:15], v[144:147], v[200:203], v[12:15]
	v_mfma_f32_16x16x32_bf16 v[8:11], v[168:171], v[200:203], v[8:11]
	v_mfma_f32_16x16x32_bf16 v[4:7], v[144:147], v[212:215], v[4:7]
	v_mfma_f32_16x16x32_bf16 v[0:3], v[168:171], v[212:215], v[0:3]
	v_mfma_f32_16x16x32_bf16 v[44:47], v[164:167], v[188:191], v[44:47]
	v_mfma_f32_16x16x32_bf16 v[40:43], v[172:175], v[188:191], v[40:43]
	v_mfma_f32_16x16x32_bf16 v[28:31], v[164:167], v[196:199], v[28:31]
	v_mfma_f32_16x16x32_bf16 v[24:27], v[172:175], v[196:199], v[24:27]
	v_mfma_f32_16x16x32_bf16 v[12:15], v[164:167], v[208:211], v[12:15]
	v_mfma_f32_16x16x32_bf16 v[8:11], v[172:175], v[208:211], v[8:11]
	v_mfma_f32_16x16x32_bf16 v[4:7], v[164:167], v[216:219], v[4:7]
	v_mfma_f32_16x16x32_bf16 v[0:3], v[172:175], v[216:219], v[0:3]
	s_barrier
	s_add_i32 s17, s17, 2
	s_add_u32 s4, s4, 0x100
	s_addc_u32 s5, s5, 0
	s_add_u32 s15, s15, 0x100
	s_addc_u32 s16, s16, 0
	s_cmp_gt_u32 s17, 29
	s_cbranch_scc0 .LBB0_96
	v_readlane_b32 s4, v249, 25
	v_readlane_b32 s5, v249, 26
	s_and_b64 vcc, exec, s[4:5]
	s_cbranch_vccz .LBB0_99
	s_barrier
